# attention unit prologue: first two key tiles DMA'd right after the Q loads (counted vmcnt adjusted)
# baseline (speedup 1.0000x reference)
.LBB0_152:
	s_or_b64 exec, exec, s[0:1]
	v_readlane_b32 s0, v254, 53
	s_waitcnt lgkmcnt(0)
	s_barrier
	v_mov_b32_e32 v0, s0
	ds_read_b32 v0, v0
	s_mov_b64 s[0:1], -1
	s_waitcnt lgkmcnt(0)
	v_readfirstlane_b32 s36, v0
	s_cmpk_gt_i32 s36, 0x77
	s_cbranch_scc1 .LBB0_149
	s_cmpk_lt_i32 s36, 0x60
	s_cbranch_scc0 .LBB0_222
	s_ashr_i32 s0, s36, 2
	s_and_b32 s0, s0, -4
	s_lshr_b32 s0, 0x405132, s0
	s_and_b32 s3, s36, 15
	s_and_b32 s5, s0, 7
	s_lshl_b32 s37, s3, 7
	v_readlane_b32 s0, v254, 37
	v_and_b32_e32 v149, 31, v148
	s_or_b32 s4, s37, s0
	s_waitcnt vmcnt(2)
	v_or_b32_e32 v48, s4, v149
	v_or_b32_e32 v1, s33, v48
	v_mov_b64_e32 v[2:3], s[72:73]
	s_movk_i32 s0, 0x1080
	v_mad_u64_u32 v[2:3], s[0:1], v1, s0, v[2:3]
	s_lshl_b32 s34, s5, 7
	v_readlane_b32 s0, v251, 13
	v_bfe_u32 v0, v148, 5, 1
	v_lshl_add_u64 v[2:3], v[2:3], 0, s[34:35]
	s_lshl_b32 s34, s0, 1
	v_lshl_add_u64 v[2:3], v[2:3], 0, s[34:35]
	v_lshlrev_b32_e32 v4, 4, v0
	v_mov_b32_e32 v5, v65
	v_lshl_add_u64 v[2:3], v[2:3], 0, v[4:5]
	v_readlane_b32 s6, v251, 31
	s_nop 3
	s_add_i32 s6, s5, s6
	s_lshl_b32 s6, s6, 3
	v_mov_b32_e32 v12, s6
	v_readlane_b32 s6, v251, 29
	v_readlane_b32 s7, v251, 30
	s_nop 4
	global_load_dwordx2 v[10:11], v12, s[6:7]
	global_load_dwordx4 v[70:73], v[2:3], off
	global_load_dwordx4 v[66:69], v[2:3], off offset:32
	v_and_b32_e32 v100, 63, v148
	v_readlane_b32 s6, v252, 9
	s_movk_i32 s7, 0x1080
	v_lshrrev_b32_e32 v101, 2, v100
	v_lshlrev_b32_e32 v103, 3, v148
	v_mov_b32_e32 v102, s6
	v_mad_u32_u24 v153, v100, s7, v102
	v_readlane_b32 s6, v251, 18
	v_readlane_b32 s7, v251, 13
	v_and_b32_e32 v103, 24, v103
	s_mul_i32 vcc_lo, s3, 0x84000
	v_or_b32_e32 v101, s6, v101
	v_mov_b32_e32 v102, s7
	s_movk_i32 s6, 0x840
	v_mad_u32_u24 v101, v101, s6, v102
	v_or_b32_e32 v101, v101, v103
	v_lshlrev_b32_e32 v154, 1, v101
	v_readlane_b32 s0, v251, 14
	v_readlane_b32 s1, v251, 15
	s_lshl_b32 s7, s5, 7
	v_readlane_b32 s6, v251, 16
	s_add_u32 s0, s0, s7
	s_addc_u32 s1, s1, 0
	v_readlane_b32 vcc_hi, v251, 17
	s_add_u32 s6, s6, s7
	s_addc_u32 s7, vcc_hi, 0
	v_add_u32_e32 v104, vcc_lo, v153
	v_add_u32_e32 v105, vcc_lo, v154
	s_add_i32 vcc_lo, vcc_lo, 0x42000
	v_add_u32_e32 v106, vcc_lo, v153
	v_add_u32_e32 v107, vcc_lo, v154
	v_readlane_b32 vcc_lo, v251, 20
	v_readlane_b32 vcc_hi, v251, 21
	s_mov_b32 m0, s25
	s_nop 0
	global_load_lds_dwordx4 v104, s[0:1]
	s_mov_b32 m0, vcc_lo
	s_nop 0
	global_load_lds_dwordx4 v105, s[6:7]
	v_readlane_b32 vcc_lo, v251, 22
	s_mov_b32 m0, vcc_hi
	s_nop 0
	global_load_lds_dwordx4 v106, s[0:1]
	s_mov_b32 m0, vcc_lo
	s_nop 0
	global_load_lds_dwordx4 v107, s[6:7]
	v_and_b32_e32 v150, 63, v148
	s_lshl_b32 s2, s5, 6
	v_cmp_eq_u32_e32 vcc, 0, v150
	s_waitcnt vmcnt(5)
	v_and_b32_e32 v2, 0xffff0000, v70
	v_lshlrev_b32_e32 v1, 16, v70
	v_mul_f32_e32 v2, v2, v2
	v_fmac_f32_e32 v2, v1, v1
	v_lshlrev_b32_e32 v1, 16, v71
	v_fmac_f32_e32 v2, v1, v1
	v_and_b32_e32 v1, 0xffff0000, v71
	v_fmac_f32_e32 v2, v1, v1
	v_lshlrev_b32_e32 v1, 16, v72
	v_fmac_f32_e32 v2, v1, v1
	v_and_b32_e32 v1, 0xffff0000, v72
	v_fmac_f32_e32 v2, v1, v1
	v_lshlrev_b32_e32 v1, 16, v73
	v_fmac_f32_e32 v2, v1, v1
	v_and_b32_e32 v1, 0xffff0000, v73
	v_fmac_f32_e32 v2, v1, v1
	s_waitcnt vmcnt(4)
	v_lshlrev_b32_e32 v1, 16, v66
	v_fmac_f32_e32 v2, v1, v1
	v_and_b32_e32 v1, 0xffff0000, v66
	v_fmac_f32_e32 v2, v1, v1
	v_lshlrev_b32_e32 v1, 16, v67
	v_fmac_f32_e32 v2, v1, v1
	v_and_b32_e32 v1, 0xffff0000, v67
	v_fmac_f32_e32 v2, v1, v1
	v_lshlrev_b32_e32 v1, 16, v68
	v_fmac_f32_e32 v2, v1, v1
	v_and_b32_e32 v1, 0xffff0000, v68
	v_fmac_f32_e32 v2, v1, v1
	v_lshlrev_b32_e32 v1, 16, v69
	v_fmac_f32_e32 v2, v1, v1
	v_and_b32_e32 v1, 0xffff0000, v69
	v_fmac_f32_e32 v2, v1, v1
	v_mov_b32_e32 v1, v2
	s_nop 1
	v_permlane32_swap_b32_e32 v2, v1
	v_add_f32_e32 v1, v2, v1
	ds_swizzle_b32 v2, v1 offset:swizzle(SWAP,1)
	s_waitcnt lgkmcnt(0)
	v_max_f32_e32 v2, v2, v2
	v_max_f32_e32 v1, v1, v2
	ds_swizzle_b32 v2, v1 offset:swizzle(SWAP,2)
	s_waitcnt lgkmcnt(0)
	v_max_f32_e32 v2, v2, v2
	v_max_f32_e32 v1, v1, v2
	ds_swizzle_b32 v2, v1 offset:swizzle(SWAP,4)
	s_waitcnt lgkmcnt(0)
	v_max_f32_e32 v2, v2, v2
	v_max_f32_e32 v1, v1, v2
	ds_swizzle_b32 v2, v1 offset:swizzle(SWAP,8)
	s_waitcnt lgkmcnt(0)
	v_max_f32_e32 v2, v2, v2
	v_max_f32_e32 v1, v1, v2
	ds_swizzle_b32 v2, v1 offset:swizzle(SWAP,16)
	s_and_saveexec_b64 s[0:1], vcc
	s_cbranch_execz .LBB0_156
	s_waitcnt lgkmcnt(0)
	v_max_f32_e32 v2, v2, v2
	v_max_f32_e32 v1, v1, v1
	v_readlane_b32 s6, v251, 12
	v_max_f32_e32 v1, v1, v2
	s_nop 0
	v_mov_b32_e32 v2, s6
	ds_write_b32 v2, v1
.LBB0_156:
	s_or_b64 exec, exec, s[0:1]
	s_lshl_b32 s0, s5, 1
	s_cmp_lt_u32 s5, 4
	v_readlane_b32 s6, v251, 31
	s_cselect_b32 s1, -2, 7
	s_add_i32 s5, s5, s6
	s_lshl_b32 s5, s5, 3
	v_readlane_b32 s6, v251, 29
	v_mov_b32_e32 v1, s5
	v_readlane_b32 s7, v251, 30
	s_waitcnt lgkmcnt(0)
	s_barrier
	v_readlane_b32 s5, v254, 54
	v_lshrrev_b32_e32 v3, 2, v150
	s_nop 0
	v_readlane_b32 s6, v252, 9
	v_mov_b32_e32 v1, s5
	v_readlane_b32 s5, v251, 13
	v_mov_b32_e32 v2, s6
	s_movk_i32 s6, 0x1080
	v_mad_u32_u24 v153, v150, s6, v2
	v_readlane_b32 s6, v251, 18
	v_mov_b32_e32 v4, s5
	s_mul_i32 s5, s3, 0x84000
	v_or_b32_e32 v2, s6, v3
	s_lshl_b32 s58, s3, 1
	s_lshr_b32 s67, s4, 6
	s_add_i32 s3, 0, 0x20800
	s_movk_i32 s4, 0x840
	v_lshlrev_b32_e32 v5, 3, v148
	v_mad_u32_u24 v13, v2, s4, v4
	v_mov_b32_e32 v2, s3
	v_and_b32_e32 v12, 24, v5
	ds_read_b128 v[2:5], v2
	ds_read_b128 v[6:9], v1
	s_sub_i32 s0, s1, s0
	v_or_b32_e32 v1, v13, v12
	v_ldexp_f32 v13, 1.0, s0
	s_waitcnt lgkmcnt(1)
	v_max_f32_e32 v5, v5, v5
	v_max_f32_e32 v4, v4, v4
	s_waitcnt lgkmcnt(0)
	v_max_f32_e32 v9, v9, v9
	v_max_f32_e32 v8, v8, v8
	v_max_f32_e32 v4, v4, v5
	v_max_f32_e32 v5, v8, v9
	v_max3_f32 v2, v2, v3, v4
	v_max3_f32 v3, v6, v7, v5
	s_mov_b32 s0, 0xf800000
	v_mul_f32_e32 v120, 0x3fb8aa3b, v13
	v_lshlrev_b32_e32 v154, 1, v1
	v_add_u32_e32 v14, s5, v153
	v_add_u32_e32 v1, s5, v154
	v_readlane_b32 s7, v252, 10
	v_readlane_b32 s7, v251, 22
	v_cvt_f32_u32_e32 v155, v48
	v_lshlrev_b32_e32 v151, 2, v0
	s_mov_b64 s[28:29], -1
	s_waitcnt vmcnt(4)
	v_mul_f32_e32 v2, v2, v10
	v_mul_f32_e32 v3, v3, v11
	v_max_f32_e32 v2, v2, v3
	v_mul_f32_e32 v3, 0x4f800000, v2
	v_cmp_gt_f32_e32 vcc, s0, v2
	s_nop 1
	v_cndmask_b32_e32 v2, v2, v3, vcc
	v_sqrt_f32_e32 v3, v2
	s_nop 0
	v_add_u32_e32 v4, -1, v3
	v_add_u32_e32 v5, 1, v3
	v_fma_f32 v6, -v4, v3, v2
	v_fma_f32 v7, -v5, v3, v2
	v_cmp_ge_f32_e64 s[0:1], 0, v6
	s_nop 1
	v_cndmask_b32_e64 v3, v3, v4, s[0:1]
	v_cmp_lt_f32_e64 s[0:1], 0, v7
	s_nop 1
	v_cndmask_b32_e64 v3, v3, v5, s[0:1]
	v_mul_f32_e32 v4, 0x37800000, v3
	v_cndmask_b32_e32 v3, v3, v4, vcc
	v_cmp_class_f32_e32 vcc, v2, v235
	s_mov_b32 s0, 0x42400000
	s_nop 0
	v_cndmask_b32_e32 v2, v3, v2, vcc
	v_mul_f32_e32 v2, 0x3f8147ae, v2
	v_cmp_gt_f32_e32 vcc, s0, v2
	v_fmaak_f32 v4, 2.0, v2, 0x43200000
	v_readfirstlane_b32 s0, v2
	v_cndmask_b32_e64 v3, 0, 1, vcc
	v_mov_b32_e32 v2, 0x43200000
	v_readfirstlane_b32 s1, v3
	s_bitcmp1_b32 s1, 0
	s_cselect_b64 vcc, -1, 0
	v_cndmask_b32_e32 v2, v4, v2, vcc
	s_lshl_b32 s34, s2, 1
	v_div_scale_f32 v4, s[2:3], v120, v120, v2
	v_rcp_f32_e32 v6, v4
	v_cndmask_b32_e64 v3, v240, 1.0, vcc
	v_div_scale_f32 v5, vcc, v2, v120, v2
	v_fma_f32 v7, -v4, v6, 1.0
	v_fmac_f32_e32 v6, v7, v6
	v_mul_f32_e32 v7, v5, v6
	v_fma_f32 v8, -v4, v7, v5
	v_fmac_f32_e32 v7, v8, v6
	v_fma_f32 v4, -v4, v7, v5
	v_div_fmas_f32 v4, v4, v6, v7
	v_div_fixup_f32 v2, v4, v120, v2
	v_add_f32_e32 v2, v3, v2
	v_min_f32_e32 v2, 0x45800000, v2
	s_and_b32 s4, s1, 1
	v_readlane_b32 s1, v251, 14
	v_cvt_i32_f32_e32 v2, v2
	s_add_u32 s2, s1, s34
	v_readlane_b32 s1, v251, 15
	s_addc_u32 s3, s1, 0
	v_readlane_b32 s1, v251, 16
	s_add_u32 s22, s1, s34
	v_readlane_b32 s1, v251, 17
	s_addc_u32 s23, s1, 0
	v_readlane_b32 s1, v251, 20
	v_sub_u32_e32 v1, s37, v2
	v_add_u32_e32 v2, s37, v2
	v_add_u32_e32 v2, 0x7f, v2
	v_ashrrev_i32_e32 v1, 6, v1
	v_ashrrev_i32_e32 v2, 6, v2
	v_max_i32_e32 v1, 0, v1
	v_min_i32_e32 v2, 31, v2
	v_readfirstlane_b32 s42, v1
	v_sub_u32_e32 v1, v2, v1
	s_or_b32 s5, s58, 1
	v_readfirstlane_b32 s1, v1
	s_add_i32 s43, s1, s42
	s_cmp_eq_u32 s58, s43
	s_cselect_b32 s48, s42, s5
	s_add_i32 s5, s48, 1
	s_mul_i32 s6, s48, 0x42000
	s_cmp_eq_u32 s48, s43
	v_add_u32_e32 v1, s6, v153
	v_add_u32_e32 v2, s6, v154
	s_cselect_b32 s5, s42, s5
	v_readlane_b32 s6, v251, 21
	s_add_i32 s6, s5, 1
	s_cmp_eq_u32 s5, s43
	s_mul_i32 s7, s5, 0x42000
	s_cselect_b32 s5, s42, s6
	s_add_i32 s6, s5, 1
	v_add_u32_e32 v1, s7, v153
	v_add_u32_e32 v2, s7, v154
	s_mov_b32 m0, s75
	s_nop 0
	global_load_lds_dwordx4 v1, s[2:3]
	v_readlane_b32 s7, v251, 23
	s_cmp_eq_u32 s5, s43
	s_mov_b32 m0, s7
	s_nop 0
	global_load_lds_dwordx4 v2, s[22:23]
	s_mul_i32 s7, s5, 0x42000
	s_cselect_b32 s5, s42, s6
	s_add_i32 s6, s5, 1
	v_add_u32_e32 v1, s7, v153
	v_add_u32_e32 v2, s7, v154
	s_mov_b32 m0, s74
	s_nop 0
	global_load_lds_dwordx4 v1, s[2:3]
	v_readlane_b32 s7, v251, 24
	s_cmp_eq_u32 s5, s43
	s_mov_b32 m0, s7
	s_nop 0
	global_load_lds_dwordx4 v2, s[22:23]
	s_mul_i32 s7, s5, 0x42000
	s_cselect_b32 s5, s42, s6
	s_add_i32 s6, s5, 1
	v_add_u32_e32 v1, s7, v153
	v_add_u32_e32 v2, s7, v154
	s_mov_b32 m0, s92
	s_nop 0
	global_load_lds_dwordx4 v1, s[2:3]
	v_readlane_b32 s7, v251, 25
	s_cmp_eq_u32 s5, s43
	s_mov_b32 m0, s7
	s_nop 0
	global_load_lds_dwordx4 v2, s[22:23]
	s_mul_i32 s7, s5, 0x42000
	s_cselect_b32 s59, s42, s6
	s_add_i32 s5, 0, 0x10000
	v_add_u32_e32 v1, s7, v153
	s_mov_b32 m0, s78
	s_nop 0
	global_load_lds_dwordx4 v1, s[2:3]
	s_cmp_eq_u32 s4, 0
	v_readlane_b32 s4, v251, 26
	v_add_u32_e32 v1, s7, v154
	s_mov_b32 m0, s4
	s_nop 0
	global_load_lds_dwordx4 v1, s[22:23]
	v_readlane_b32 s4, v251, 27
	v_lshlrev_b32_e32 v2, 4, v149
	s_nop 0
	v_or_b32_e32 v1, s4, v0
	v_lshlrev_b32_e32 v1, 10, v1
	v_add3_u32 v156, 0, v1, v2
	v_lshlrev_b32_e32 v1, 1, v148
	v_lshrrev_b32_e32 v0, 2, v148
	v_and_b32_e32 v1, 32, v1
	v_and_or_b32 v0, v0, 3, v151
	v_add_u32_e32 v1, s5, v1
	v_lshlrev_b32_e32 v0, 6, v0
	v_add3_u32 v152, v1, v12, v0
	s_cbranch_scc0 .LBB0_196
	s_waitcnt vmcnt(10)
	s_barrier
	s_mul_i32 s4, s59, 0x42000
	v_add_u32_e32 v0, s4, v153
	s_mov_b32 m0, s80
	s_nop 0
	global_load_lds_dwordx4 v0, s[2:3]
	v_add_u32_e32 v0, s4, v154
	v_readlane_b32 s4, v251, 28
	s_mov_b32 m0, s4
	s_nop 0
	global_load_lds_dwordx4 v0, s[22:23]
	ds_read_b128 v[44:47], v156
	ds_read_b128 v[36:39], v156 offset:512
	ds_read_b128 v[32:35], v156 offset:2048
	ds_read_b128 v[40:43], v156 offset:2560
	v_or_b32_e32 v0, s37, v151
	v_sub_u32_e32 v48, v0, v48
	v_cvt_f32_i32_e32 v49, v48
	s_cmp_lg_u32 s58, s67
	s_cbranch_scc0 .LBB0_159
	s_cmp_gt_u32 s58, s67
	s_cselect_b64 s[4:5], -1, 0
	v_cndmask_b32_e64 v4, v120, -v120, s[4:5]
	s_mov_b32 s4, 2.0
	v_mul_f32_e32 v0, v4, v49
	v_fma_f32 v1, v4, v49, v4
	s_mov_b32 s5, 0x40400000
	v_pk_fma_f32 v[2:3], v[4:5], s[4:5], v[0:1] op_sel_hi:[0,1,0]
	v_mul_f32_e32 v14, 0x41000000, v4
	v_mul_f32_e32 v28, 0x42000000, v4
	v_pk_add_f32 v[4:5], v[14:15], v[0:1] op_sel_hi:[0,1]
	v_pk_add_f32 v[6:7], v[14:15], v[2:3] op_sel_hi:[0,1]
	v_pk_add_f32 v[8:9], v[14:15], v[4:5] op_sel_hi:[0,1]
	v_pk_add_f32 v[10:11], v[14:15], v[6:7] op_sel_hi:[0,1]
	v_pk_add_f32 v[12:13], v[14:15], v[8:9] op_sel_hi:[0,1]
	v_pk_add_f32 v[14:15], v[14:15], v[10:11] op_sel_hi:[0,1]
	v_pk_add_f32 v[18:19], v[28:29], v[2:3] op_sel_hi:[0,1]
	v_pk_add_f32 v[22:23], v[28:29], v[6:7] op_sel_hi:[0,1]
	v_pk_add_f32 v[26:27], v[28:29], v[10:11] op_sel_hi:[0,1]
	v_pk_add_f32 v[30:31], v[28:29], v[14:15] op_sel_hi:[0,1]
	v_pk_add_f32 v[16:17], v[28:29], v[0:1] op_sel_hi:[0,1]
	v_pk_add_f32 v[20:21], v[28:29], v[4:5] op_sel_hi:[0,1]
	v_pk_add_f32 v[24:25], v[28:29], v[8:9] op_sel_hi:[0,1]
	v_pk_add_f32 v[28:29], v[28:29], v[12:13] op_sel_hi:[0,1]
	s_mov_b64 s[28:29], 0
